# w_up conversion moved out of the out-proj tail into the slack of waves 1-3 of the prompt-scan chunk loops (one 64x32 strip per wave per chunk, no LDS)
# speedup vs baseline: 1.0483x; 1.0120x over previous
; __device__ __forceinline__ unsigned pack2(float lo, float hi) { unsigned r; asm("v_cvt_pk_bf16_f32 %0, %1, %2" : "=v"(r) : "v"(lo), "v"(hi)); return r; }
; __device__ __forceinline__ void tile_load(const TileRef& r, f32x4 (&v)[8], int tid) {
;     const int nc = (tid & 63) * 4, n = r.nt * 256 + nc;
; #pragma unroll
;     for (int i = 0; i < 8; ++i) {
;         const int kr = (tid >> 6) + 8 * i;
;         v[i] = (f32x4){0.f, 0.f, 0.f, 0.f};
;         if (n < r.N) v[i] = __builtin_nontemporal_load((const f32x4*)(r.W + (size_t)(r.kt * 64 + kr) * r.N + n));
;     }
; }
; __device__ __forceinline__ void tile_lds_write(const f32x4 (&v)[8], int tid, unsigned char* smem) {
;     float* tile = (float*)smem;
;     const int nc = (tid & 63) * 4;
; #pragma unroll
;     for (int i = 0; i < 8; ++i) {
;         const int kr = (tid >> 6) + 8 * i;
;         tile[kr * 257 + nc] = v[i][0]; tile[kr * 257 + nc + 1] = v[i][1]; tile[kr * 257 + nc + 2] = v[i][2]; tile[kr * 257 + nc + 3] = v[i][3];
;     }
; }
; __device__ __forceinline__ void tile_store(const TileRef& r, int tid, unsigned char* smem) {
;     const float* tile = (const float*)smem;
;     const int kc = (tid & 7) * 8;
; #pragma unroll
;     for (int q = 0; q < 4; ++q) {
;         const int nr = (tid >> 3) + 64 * q;
;         u32x4 o;
;         o[0] = pack2(tile[(kc + 0) * 257 + nr], tile[(kc + 1) * 257 + nr]); o[1] = pack2(tile[(kc + 2) * 257 + nr], tile[(kc + 3) * 257 + nr]);
;         o[2] = pack2(tile[(kc + 4) * 257 + nr], tile[(kc + 5) * 257 + nr]); o[3] = pack2(tile[(kc + 6) * 257 + nr], tile[(kc + 7) * 257 + nr]);
;         *(u32x4*)(r.WT + (size_t)(r.nt * 256 + nr) * r.K + r.kt * 64 + kc) = o;
;     }
; }
; template <bool ML>
; __device__ __forceinline__ void prompt_scan(const Params& p, unsigned char* smem, int job) {
;     ...
;     for (int c = 0; c < NCH; ++c) {
;         int tid = tid_outer; asm volatile("" : "+v"(tid));
;         const int lane = tid & 63, fr = lane & 15, fq = lane >> 4;
;         const int p0 = c == 0 ? 0 : 16 + (c - 1) * CHL, Lv = c == 0 ? 16 : CHL;
;         float* sc = scb + (c & 1) * 800;
;         float *rowv = sc, *colv = sc + 128, *colm = sc + 256, *ev = sc + 384, *scv = sc + 512, *dden = sc + 640, *misc = sc + 768;
;         if (wid == 0 && c + 1 < NCH) scal_load(c + 1);
.LBB0_499:
	v_readfirstlane_b32 s1, v151
	s_lshr_b32 s1, s1, 6
	s_add_i32 s1, s1, -1
	s_cmp_gt_u32 s1, 2
	s_cbranch_scc1 .Lcs_ml_done
	s_add_i32 s0, s3, 0x70
	s_ashr_i32 s0, s0, 7
	s_mul_i32 s0, s0, 3
	s_add_i32 s0, s0, s1
	v_and_b32_e32 v248, 7, v151
	v_bfe_u32 v249, v151, 3, 3
	v_mul_u32_u24_e32 v246, 0x58000, v248
	v_lshl_add_u32 v246, v249, 4, v246
	v_lshlrev_b32_e32 v247, 14, v249
	v_lshl_add_u32 v247, v248, 4, v247
	s_add_i32 s1, s0, -3
	s_cmp_lt_i32 s1, 0
	s_cbranch_scc1 .Lcs_ml_load
	v_readlane_b32 s98, v254, 0
	s_nop 0
	s_cmpk_lt_u32 s98, 0x80
	s_cselect_b32 s99, 48, 40
	s_cmp_ge_u32 s1, s99
	s_cbranch_scc1 .Lcs_ml_done
	s_lshr_b32 s99, s1, 3
	s_and_b32 s1, s1, 7
	s_lshl_b32 s99, s99, 8
	s_add_i32 s99, s99, s98
	s_lshl_b32 s1, s1, 17
	s_lshr_b32 s98, s99, 5
	s_lshl_b32 s98, s98, 20
	s_add_i32 s1, s1, s98
	s_and_b32 s99, s99, 31
	s_lshl_b32 s99, s99, 7
	s_add_i32 s1, s1, s99
	v_add_u32_e32 v250, s1, v247
	v_readlane_b32 s98, v254, 28
	v_readlane_b32 s99, v254, 29
	v_add_u32_e32 v251, 0x1000, v250
	v_add_u32_e32 v252, 0x2000, v250
	v_add_u32_e32 v253, 0x3000, v250
	s_add_u32 s98, s98, 0x3b00000
	s_addc_u32 s99, s99, 0
	s_waitcnt vmcnt(0)
	v_cvt_pk_bf16_f32 v174, v214, v218
	v_cvt_pk_bf16_f32 v175, v222, v226
	v_cvt_pk_bf16_f32 v176, v230, v234
	v_cvt_pk_bf16_f32 v177, v238, v242
	v_cvt_pk_bf16_f32 v178, v215, v219
	v_cvt_pk_bf16_f32 v179, v223, v227
	v_cvt_pk_bf16_f32 v180, v231, v235
	v_cvt_pk_bf16_f32 v181, v239, v243
	v_cvt_pk_bf16_f32 v182, v216, v220
	v_cvt_pk_bf16_f32 v183, v224, v228
	v_cvt_pk_bf16_f32 v184, v232, v236
	v_cvt_pk_bf16_f32 v185, v240, v244
	v_cvt_pk_bf16_f32 v186, v217, v221
	v_cvt_pk_bf16_f32 v187, v225, v229
	v_cvt_pk_bf16_f32 v188, v233, v237
	v_cvt_pk_bf16_f32 v189, v241, v245
	global_store_dwordx4 v250, v[174:177], s[98:99]
	global_store_dwordx4 v251, v[178:181], s[98:99]
	global_store_dwordx4 v252, v[182:185], s[98:99]
	global_store_dwordx4 v253, v[186:189], s[98:99]
.Lcs_ml_load:
	v_readlane_b32 s98, v254, 0
	s_nop 0
	s_cmpk_lt_u32 s98, 0x80
	s_cselect_b32 s99, 48, 40
	s_cmp_ge_u32 s0, s99
	s_cbranch_scc1 .Lcs_ml_done
	s_lshr_b32 s99, s0, 3
	s_and_b32 s1, s0, 7
	s_lshl_b32 s99, s99, 8
	s_add_i32 s99, s99, s98
	s_lshl_b32 s1, s1, 7
	s_lshr_b32 s98, s99, 5
	s_lshl_b32 s98, s98, 10
	s_add_i32 s1, s1, s98
	s_and_b32 s99, s99, 31
	s_mul_i32 s99, s99, 0x2c0000
	s_add_i32 s1, s1, s99
	v_readlane_b32 s98, v255, 23
	v_readlane_b32 s99, v255, 24
	v_add_u32_e32 v250, s1, v246
	v_add_u32_e32 v251, 0xb000, v250
	v_add_u32_e32 v252, 0x16000, v250
	v_add_u32_e32 v253, 0x21000, v250
	s_nop 1
	global_load_dwordx4 v[214:217], v250, s[98:99] nt
	global_load_dwordx4 v[218:221], v251, s[98:99] nt
	global_load_dwordx4 v[222:225], v252, s[98:99] nt
	global_load_dwordx4 v[226:229], v253, s[98:99] nt
	v_add_u32_e32 v250, 0x2c000, v250
	v_add_u32_e32 v251, 0x2c000, v251
	v_add_u32_e32 v252, 0x2c000, v252
	v_add_u32_e32 v253, 0x2c000, v253
	global_load_dwordx4 v[230:233], v250, s[98:99] nt
	global_load_dwordx4 v[234:237], v251, s[98:99] nt
	global_load_dwordx4 v[238:241], v252, s[98:99] nt
	global_load_dwordx4 v[242:245], v253, s[98:99] nt

; __device__ __forceinline__ unsigned pack2(float lo, float hi) { unsigned r; asm("v_cvt_pk_bf16_f32 %0, %1, %2" : "=v"(r) : "v"(lo), "v"(hi)); return r; }
; __device__ __forceinline__ void tile_load(const TileRef& r, f32x4 (&v)[8], int tid) {
;     const int nc = (tid & 63) * 4, n = r.nt * 256 + nc;
; #pragma unroll
;     for (int i = 0; i < 8; ++i) {
;         const int kr = (tid >> 6) + 8 * i;
;         v[i] = (f32x4){0.f, 0.f, 0.f, 0.f};
;         if (n < r.N) v[i] = __builtin_nontemporal_load((const f32x4*)(r.W + (size_t)(r.kt * 64 + kr) * r.N + n));
;     }
; }
; __device__ __forceinline__ void tile_lds_write(const f32x4 (&v)[8], int tid, unsigned char* smem) {
;     float* tile = (float*)smem;
;     const int nc = (tid & 63) * 4;
; #pragma unroll
;     for (int i = 0; i < 8; ++i) {
;         const int kr = (tid >> 6) + 8 * i;
;         tile[kr * 257 + nc] = v[i][0]; tile[kr * 257 + nc + 1] = v[i][1]; tile[kr * 257 + nc + 2] = v[i][2]; tile[kr * 257 + nc + 3] = v[i][3];
;     }
; }
; __device__ __forceinline__ void tile_store(const TileRef& r, int tid, unsigned char* smem) {
;     const float* tile = (const float*)smem;
;     const int kc = (tid & 7) * 8;
; #pragma unroll
;     for (int q = 0; q < 4; ++q) {
;         const int nr = (tid >> 3) + 64 * q;
;         u32x4 o;
;         o[0] = pack2(tile[(kc + 0) * 257 + nr], tile[(kc + 1) * 257 + nr]); o[1] = pack2(tile[(kc + 2) * 257 + nr], tile[(kc + 3) * 257 + nr]);
;         o[2] = pack2(tile[(kc + 4) * 257 + nr], tile[(kc + 5) * 257 + nr]); o[3] = pack2(tile[(kc + 6) * 257 + nr], tile[(kc + 7) * 257 + nr]);
;         *(u32x4*)(r.WT + (size_t)(r.nt * 256 + nr) * r.K + r.kt * 64 + kc) = o;
;     }
; }
; template <bool ML>
; __device__ __forceinline__ void prompt_scan(const Params& p, unsigned char* smem, int job) {
;     ...
;     for (int c = 0; c < NCH; ++c) {
;         int tid = tid_outer; asm volatile("" : "+v"(tid));
;         const int lane = tid & 63, fr = lane & 15, fq = lane >> 4;
;         const int p0 = c == 0 ? 0 : 16 + (c - 1) * CHL, Lv = c == 0 ? 16 : CHL;
;         float* sc = scb + (c & 1) * 800;
;         float *rowv = sc, *colv = sc + 128, *colm = sc + 256, *ev = sc + 384, *scv = sc + 512, *dden = sc + 640, *misc = sc + 768;
;         if (wid == 0 && c + 1 < NCH) scal_load(c + 1);
.LBB0_653:
	v_readfirstlane_b32 s31, v151
	s_lshr_b32 s31, s31, 6
	s_add_i32 s31, s31, -1
	s_cmp_gt_u32 s31, 2
	s_cbranch_scc1 .Lcs_ssd_done
	s_add_i32 s30, s46, 0x70
	s_ashr_i32 s30, s30, 7
	s_mul_i32 s30, s30, 3
	s_add_i32 s30, s30, s31
	v_and_b32_e32 v248, 7, v151
	v_bfe_u32 v249, v151, 3, 3
	v_mul_u32_u24_e32 v246, 0x58000, v248
	v_lshl_add_u32 v246, v249, 4, v246
	v_lshlrev_b32_e32 v247, 14, v249
	v_lshl_add_u32 v247, v248, 4, v247
	s_add_i32 s31, s30, -3
	s_cmp_lt_i32 s31, 0
	s_cbranch_scc1 .Lcs_ssd_load
	v_readlane_b32 s98, v254, 0
	s_nop 0
	s_cmpk_lt_u32 s98, 0x80
	s_cselect_b32 s99, 48, 40
	s_cmp_ge_u32 s31, s99
	s_cbranch_scc1 .Lcs_ssd_done
	s_lshr_b32 s99, s31, 3
	s_and_b32 s31, s31, 7
	s_lshl_b32 s99, s99, 8
	s_add_i32 s99, s99, s98
	s_lshl_b32 s31, s31, 17
	s_lshr_b32 s98, s99, 5
	s_lshl_b32 s98, s98, 20
	s_add_i32 s31, s31, s98
	s_and_b32 s99, s99, 31
	s_lshl_b32 s99, s99, 7
	s_add_i32 s31, s31, s99
	v_add_u32_e32 v250, s31, v247
	v_readlane_b32 s98, v254, 28
	v_readlane_b32 s99, v254, 29
	v_add_u32_e32 v251, 0x1000, v250
	v_add_u32_e32 v252, 0x2000, v250
	v_add_u32_e32 v253, 0x3000, v250
	s_add_u32 s98, s98, 0x3b00000
	s_addc_u32 s99, s99, 0
	s_waitcnt vmcnt(0)
	v_cvt_pk_bf16_f32 v174, v214, v218
	v_cvt_pk_bf16_f32 v175, v222, v226
	v_cvt_pk_bf16_f32 v176, v230, v234
	v_cvt_pk_bf16_f32 v177, v238, v242
	v_cvt_pk_bf16_f32 v178, v215, v219
	v_cvt_pk_bf16_f32 v179, v223, v227
	v_cvt_pk_bf16_f32 v180, v231, v235
	v_cvt_pk_bf16_f32 v181, v239, v243
	v_cvt_pk_bf16_f32 v182, v216, v220
	v_cvt_pk_bf16_f32 v183, v224, v228
	v_cvt_pk_bf16_f32 v184, v232, v236
	v_cvt_pk_bf16_f32 v185, v240, v244
	v_cvt_pk_bf16_f32 v186, v217, v221
	v_cvt_pk_bf16_f32 v187, v225, v229
	v_cvt_pk_bf16_f32 v188, v233, v237
	v_cvt_pk_bf16_f32 v189, v241, v245
	global_store_dwordx4 v250, v[174:177], s[98:99]
	global_store_dwordx4 v251, v[178:181], s[98:99]
	global_store_dwordx4 v252, v[182:185], s[98:99]
	global_store_dwordx4 v253, v[186:189], s[98:99]
.Lcs_ssd_load:
	v_readlane_b32 s98, v254, 0
	s_nop 0
	s_cmpk_lt_u32 s98, 0x80
	s_cselect_b32 s99, 48, 40
	s_cmp_ge_u32 s30, s99
	s_cbranch_scc1 .Lcs_ssd_done
	s_lshr_b32 s99, s30, 3
	s_and_b32 s31, s30, 7
	s_lshl_b32 s99, s99, 8
	s_add_i32 s99, s99, s98
	s_lshl_b32 s31, s31, 7
	s_lshr_b32 s98, s99, 5
	s_lshl_b32 s98, s98, 10
	s_add_i32 s31, s31, s98
	s_and_b32 s99, s99, 31
	s_mul_i32 s99, s99, 0x2c0000
	s_add_i32 s31, s31, s99
	v_readlane_b32 s98, v255, 23
	v_readlane_b32 s99, v255, 24
	v_add_u32_e32 v250, s31, v246
	v_add_u32_e32 v251, 0xb000, v250
	v_add_u32_e32 v252, 0x16000, v250
	v_add_u32_e32 v253, 0x21000, v250
	s_nop 1
	global_load_dwordx4 v[214:217], v250, s[98:99] nt
	global_load_dwordx4 v[218:221], v251, s[98:99] nt
	global_load_dwordx4 v[222:225], v252, s[98:99] nt
	global_load_dwordx4 v[226:229], v253, s[98:99] nt
	v_add_u32_e32 v250, 0x2c000, v250
	v_add_u32_e32 v251, 0x2c000, v251
	v_add_u32_e32 v252, 0x2c000, v252
	v_add_u32_e32 v253, 0x2c000, v253
	global_load_dwordx4 v[230:233], v250, s[98:99] nt
	global_load_dwordx4 v[234:237], v251, s[98:99] nt
	global_load_dwordx4 v[238:241], v252, s[98:99] nt
	global_load_dwordx4 v[242:245], v253, s[98:99] nt
